# v17 + PV-phase priority held until after the tile's last two PV MFMAs (priolate), placement kept
# baseline (speedup 1.0000x reference)
.LqL_ldsb:
	s_add_i32 s33, s65, 0x10000
	s_and_b32 s33, s33, 0x18000
	s_add_i32 s33, s57, s33
	v_lshlrev_b32_e32 v198, 1, v150
	v_mfma_f32_32x32x16_bf16 v[32:47], v[242:245], v[64:67], v[32:47]
	s_mov_b32 m0, s33
	v_exp_f32_e32 v72, v72
	v_exp_f32_e32 v73, v73
	v_exp_f32_e32 v74, v74
	v_exp_f32_e32 v75, v75
	v_add_f32_e32 v184, v72, v73
	s_and_b32 s100, s65, 0x18000
	v_add_u32_e32 v194, s100, v149
	v_add_u32_e32 v195, v194, v157
	v_add_u32_e32 v196, v194, v193
	ds_read_b128 v[242:245], v218 offset:16384
	global_load_lds_dwordx4 v188, s[70:71]
	v_mfma_f32_32x32x16_bf16 v[48:63], v[246:249], v[64:67], v[48:63]
	v_exp_f32_e32 v76, v76
	v_exp_f32_e32 v77, v77
	v_cvt_pk_bf16_f32 v68, v72, v73
	v_add_f32_e32 v185, v74, v75
	v_cvt_pk_bf16_f32 v69, v74, v75
	v_add_u32_e32 v197, v194, v208
	v_add_u32_e32 v194, v194, v209
	ds_read_b128 v[132:135], v195
	ds_read_b128 v[116:119], v195 offset:4096
	ds_read_b128 v[246:249], v218 offset:20480
	v_mfma_f32_32x32x16_bf16 v[16:31], v[250:253], v[64:67], v[16:31]
	s_add_u32 s100, s70, 0x40000
	s_addc_u32 s101, s71, 0
	s_add_i32 m0, s33, 0x2000
	v_exp_f32_e32 v78, v78
	v_exp_f32_e32 v79, v79
	v_add_f32_e32 v186, v76, v77
	v_cvt_pk_bf16_f32 v70, v76, v77
	v_add_f32_e32 v184, v184, v185
	ds_read_b128 v[136:139], v196
	ds_read_b128 v[120:123], v196 offset:4096
	ds_read_b128 v[140:143], v197
	ds_read_b128 v[124:127], v197 offset:4096
	ds_read_b128 v[250:253], v218 offset:24576
	global_load_lds_dwordx4 v188, s[100:101]
	v_mfma_f32_32x32x16_bf16 v[0:15], v[200:203], v[64:67], v[0:15]
	v_add_f32_e32 v187, v78, v79
	v_cvt_pk_bf16_f32 v71, v78, v79
	v_add_f32_e32 v186, v186, v187
	v_add_f32_e32 v184, v184, v186
	v_add_f32_e32 v206, v206, v184
	ds_read_b128 v[128:131], v194
	ds_read_b128 v[112:115], v194 offset:4096
	ds_read_b128 v[200:203], v218 offset:28672
	v_mfma_f32_32x32x16_bf16 v[32:47], v[220:223], v[68:71], v[32:47]
	s_add_i32 m0, s33, 0x4000
	v_exp_f32_e32 v80, v80
	v_exp_f32_e32 v81, v81
	v_exp_f32_e32 v82, v82
	v_exp_f32_e32 v83, v83
	v_add_f32_e32 v184, v80, v81
	ds_read_b128 v[220:223], v219 offset:16384
	global_load_lds_dwordx4 v198, s[66:67]
	v_mfma_f32_32x32x16_bf16 v[48:63], v[224:227], v[68:71], v[48:63]
	v_exp_f32_e32 v84, v84
	v_exp_f32_e32 v85, v85
	v_cvt_pk_bf16_f32 v72, v80, v81
	v_add_f32_e32 v185, v82, v83
	v_cvt_pk_bf16_f32 v73, v82, v83
	ds_read_b128 v[224:227], v219 offset:20480
	v_mfma_f32_32x32x16_bf16 v[16:31], v[234:237], v[68:71], v[16:31]
	s_add_u32 s100, s66, 0x40000
	s_addc_u32 s101, s67, 0
	s_add_i32 m0, s33, 0x6000
	v_exp_f32_e32 v86, v86
	v_exp_f32_e32 v87, v87
	v_add_f32_e32 v186, v84, v85
	v_cvt_pk_bf16_f32 v74, v84, v85
	v_add_f32_e32 v184, v184, v185
	ds_read_b128 v[234:237], v219 offset:24576
	global_load_lds_dwordx4 v198, s[100:101]
	v_mfma_f32_32x32x16_bf16 v[0:15], v[238:241], v[68:71], v[0:15]
	v_add_f32_e32 v187, v86, v87
	v_cvt_pk_bf16_f32 v75, v86, v87
	v_add_f32_e32 v186, v186, v187
	v_add_f32_e32 v184, v184, v186
	v_add_f32_e32 v206, v206, v184
	ds_read_b128 v[238:241], v219 offset:28672
	s_waitcnt lgkmcnt(4)
	v_mfma_f32_32x32x16_bf16 v[32:47], v[242:245], v[72:75], v[32:47]
	s_add_u32 s100, s70, 0x1000
	s_addc_u32 s101, s71, 0
	s_add_i32 m0, s33, 0x1000
	v_exp_f32_e32 v88, v88
	v_exp_f32_e32 v89, v89
	v_exp_f32_e32 v90, v90
	v_exp_f32_e32 v91, v91
	v_add_f32_e32 v184, v88, v89
	global_load_lds_dwordx4 v188, s[100:101]
	v_mfma_f32_32x32x16_bf16 v[48:63], v[246:249], v[72:75], v[48:63]
	v_exp_f32_e32 v92, v92
	v_exp_f32_e32 v93, v93
	v_cvt_pk_bf16_f32 v76, v88, v89
	v_add_f32_e32 v185, v90, v91
	v_cvt_pk_bf16_f32 v77, v90, v91
	v_mfma_f32_32x32x16_bf16 v[16:31], v[250:253], v[72:75], v[16:31]
	s_add_u32 s100, s70, 0x41000
	s_addc_u32 s101, s71, 0
	s_add_i32 m0, s33, 0x3000
	v_exp_f32_e32 v94, v94
	v_exp_f32_e32 v95, v95
	v_add_f32_e32 v186, v92, v93
	v_cvt_pk_bf16_f32 v78, v92, v93
	v_add_f32_e32 v184, v184, v185
	global_load_lds_dwordx4 v188, s[100:101]
	v_mfma_f32_32x32x16_bf16 v[0:15], v[200:203], v[72:75], v[0:15]
	v_add_f32_e32 v187, v94, v95
	v_cvt_pk_bf16_f32 v79, v94, v95
	v_add_f32_e32 v186, v186, v187
	v_add_f32_e32 v184, v184, v186
	v_add_f32_e32 v206, v206, v184
	s_waitcnt lgkmcnt(0)
	v_mfma_f32_32x32x16_bf16 v[32:47], v[220:223], v[76:79], v[32:47]
	s_add_u32 s100, s66, 0x20000
	s_addc_u32 s101, s67, 0
	s_add_i32 m0, s33, 0x5000
	s_nop 0
	global_load_lds_dwordx4 v198, s[100:101]
	v_mfma_f32_32x32x16_bf16 v[48:63], v[224:227], v[76:79], v[48:63]
	s_add_u32 s100, s66, 0x60000
	s_addc_u32 s101, s67, 0
	s_add_i32 m0, s33, 0x7000
	s_nop 0
	global_load_lds_dwordx4 v198, s[100:101]
	s_waitcnt lgkmcnt(0)
	s_add_i32 s65, s65, 0x8000
	s_addk_i32 s23, 0x100
	s_add_i32 s36, s36, 64
	s_mov_b32 s33, s54
	s_cmpk_eq_i32 s23, 0x1e00
	v_mfma_f32_32x32x16_bf16 v[16:31], v[234:237], v[76:79], v[16:31]
	v_mfma_f32_32x32x16_bf16 v[0:15], v[238:241], v[76:79], v[0:15]
	s_setprio 0
	s_cbranch_scc0 .LqL_top
	s_branch .LBB0_284

.LqT_g0:
	v_exp_f32_e32 v64, v64
	v_exp_f32_e32 v65, v65
	v_exp_f32_e32 v66, v66
	v_exp_f32_e32 v67, v67
	v_add_f32_e32 v184, v64, v65
	v_exp_f32_e32 v68, v68
	v_exp_f32_e32 v69, v69
	v_cvt_pk_bf16_f32 v64, v64, v65
	v_add_f32_e32 v185, v66, v67
	v_cvt_pk_bf16_f32 v65, v66, v67
	v_exp_f32_e32 v70, v70
	v_exp_f32_e32 v71, v71
	v_add_f32_e32 v186, v68, v69
	v_cvt_pk_bf16_f32 v66, v68, v69
	v_add_f32_e32 v184, v184, v185
	v_add_f32_e32 v187, v70, v71
	v_cvt_pk_bf16_f32 v67, v70, v71
	v_add_f32_e32 v186, v186, v187
	v_add_f32_e32 v184, v184, v186
	v_add_f32_e32 v206, v206, v184
	s_waitcnt vmcnt(0) lgkmcnt(0)
	s_add_i32 s54, s33, 1
	s_setprio 1
	v_mfma_f32_32x32x16_bf16 v[32:47], v[242:245], v[64:67], v[32:47]
	v_exp_f32_e32 v72, v72
	v_exp_f32_e32 v73, v73
	v_exp_f32_e32 v74, v74
	v_exp_f32_e32 v75, v75
	v_add_f32_e32 v184, v72, v73
	s_and_b32 s100, s65, 0x18000
	v_add_u32_e32 v194, s100, v149
	v_add_u32_e32 v195, v194, v157
	v_add_u32_e32 v196, v194, v193
	ds_read_b128 v[242:245], v218 offset:16384
	v_mfma_f32_32x32x16_bf16 v[48:63], v[246:249], v[64:67], v[48:63]
	v_exp_f32_e32 v76, v76
	v_exp_f32_e32 v77, v77
	v_cvt_pk_bf16_f32 v68, v72, v73
	v_add_f32_e32 v185, v74, v75
	v_cvt_pk_bf16_f32 v69, v74, v75
	v_add_u32_e32 v197, v194, v208
	v_add_u32_e32 v194, v194, v209
	ds_read_b128 v[132:135], v195
	ds_read_b128 v[116:119], v195 offset:4096
	ds_read_b128 v[246:249], v218 offset:20480
	v_mfma_f32_32x32x16_bf16 v[16:31], v[250:253], v[64:67], v[16:31]
	v_exp_f32_e32 v78, v78
	v_exp_f32_e32 v79, v79
	v_add_f32_e32 v186, v76, v77
	v_cvt_pk_bf16_f32 v70, v76, v77
	v_add_f32_e32 v184, v184, v185
	ds_read_b128 v[136:139], v196
	ds_read_b128 v[120:123], v196 offset:4096
	ds_read_b128 v[140:143], v197
	ds_read_b128 v[124:127], v197 offset:4096
	ds_read_b128 v[250:253], v218 offset:24576
	v_mfma_f32_32x32x16_bf16 v[0:15], v[200:203], v[64:67], v[0:15]
	v_add_f32_e32 v187, v78, v79
	v_cvt_pk_bf16_f32 v71, v78, v79
	v_add_f32_e32 v186, v186, v187
	v_add_f32_e32 v184, v184, v186
	v_add_f32_e32 v206, v206, v184
	ds_read_b128 v[128:131], v194
	ds_read_b128 v[112:115], v194 offset:4096
	ds_read_b128 v[200:203], v218 offset:28672
	v_mfma_f32_32x32x16_bf16 v[32:47], v[220:223], v[68:71], v[32:47]
	v_exp_f32_e32 v80, v80
	v_exp_f32_e32 v81, v81
	v_exp_f32_e32 v82, v82
	v_exp_f32_e32 v83, v83
	v_add_f32_e32 v184, v80, v81
	ds_read_b128 v[220:223], v219 offset:16384
	v_mfma_f32_32x32x16_bf16 v[48:63], v[224:227], v[68:71], v[48:63]
	v_exp_f32_e32 v84, v84
	v_exp_f32_e32 v85, v85
	v_cvt_pk_bf16_f32 v72, v80, v81
	v_add_f32_e32 v185, v82, v83
	v_cvt_pk_bf16_f32 v73, v82, v83
	ds_read_b128 v[224:227], v219 offset:20480
	v_mfma_f32_32x32x16_bf16 v[16:31], v[234:237], v[68:71], v[16:31]
	v_exp_f32_e32 v86, v86
	v_exp_f32_e32 v87, v87
	v_add_f32_e32 v186, v84, v85
	v_cvt_pk_bf16_f32 v74, v84, v85
	v_add_f32_e32 v184, v184, v185
	ds_read_b128 v[234:237], v219 offset:24576
	v_mfma_f32_32x32x16_bf16 v[0:15], v[238:241], v[68:71], v[0:15]
	v_add_f32_e32 v187, v86, v87
	v_cvt_pk_bf16_f32 v75, v86, v87
	v_add_f32_e32 v186, v186, v187
	v_add_f32_e32 v184, v184, v186
	v_add_f32_e32 v206, v206, v184
	ds_read_b128 v[238:241], v219 offset:28672
	s_waitcnt lgkmcnt(4)
	v_mfma_f32_32x32x16_bf16 v[32:47], v[242:245], v[72:75], v[32:47]
	v_exp_f32_e32 v88, v88
	v_exp_f32_e32 v89, v89
	v_exp_f32_e32 v90, v90
	v_exp_f32_e32 v91, v91
	v_add_f32_e32 v184, v88, v89
	v_mfma_f32_32x32x16_bf16 v[48:63], v[246:249], v[72:75], v[48:63]
	v_exp_f32_e32 v92, v92
	v_exp_f32_e32 v93, v93
	v_cvt_pk_bf16_f32 v76, v88, v89
	v_add_f32_e32 v185, v90, v91
	v_cvt_pk_bf16_f32 v77, v90, v91
	v_mfma_f32_32x32x16_bf16 v[16:31], v[250:253], v[72:75], v[16:31]
	v_exp_f32_e32 v94, v94
	v_exp_f32_e32 v95, v95
	v_add_f32_e32 v186, v92, v93
	v_cvt_pk_bf16_f32 v78, v92, v93
	v_add_f32_e32 v184, v184, v185
	v_mfma_f32_32x32x16_bf16 v[0:15], v[200:203], v[72:75], v[0:15]
	v_add_f32_e32 v187, v94, v95
	v_cvt_pk_bf16_f32 v79, v94, v95
	v_add_f32_e32 v186, v186, v187
	v_add_f32_e32 v184, v184, v186
	v_add_f32_e32 v206, v206, v184
	s_waitcnt lgkmcnt(0)
	v_mfma_f32_32x32x16_bf16 v[32:47], v[220:223], v[76:79], v[32:47]
	v_mfma_f32_32x32x16_bf16 v[48:63], v[224:227], v[76:79], v[48:63]
	s_waitcnt lgkmcnt(0)
	s_barrier
	s_add_i32 s65, s65, 0x8000
	s_addk_i32 s23, 0x100
	s_add_i32 s36, s36, 64
	s_mov_b32 s33, s54
	s_cmpk_eq_i32 s23, 0x1e00
	v_mfma_f32_32x32x16_bf16 v[16:31], v[234:237], v[76:79], v[16:31]
	v_mfma_f32_32x32x16_bf16 v[0:15], v[238:241], v[76:79], v[0:15]
	s_setprio 0
	s_cbranch_scc0 .LqT_top
	s_branch .LBB0_284
